# E62: E60 plus diff attention first tile copy: nine exp2 slices re-spaced three per gap behind QK MFMAs c/d/e (first result renamed to v202)
# speedup vs baseline: 1.0060x; 1.0060x over previous
; __device__ __forceinline__ void finishSM(f32x16& p0, f32x16& p1, float alpha, float& l_reg, bf16x8& pa0, bf16x8& pa1, bf16x8& pa2, bf16x8& pa3) {
; #pragma unroll
;   for (int r = 0; r < 16; ++r) p1[r] = __builtin_amdgcn_exp2f(p1[r]);
;   float ps = 0;
; #pragma unroll
;   for (int r = 0; r < 16; ++r) ps += p0[r];
; #pragma unroll
;   for (int r = 0; r < 16; ++r) ps += p1[r];
;   { auto rr = __builtin_amdgcn_permlane32_swap(__float_as_uint(ps), __float_as_uint(ps), false, false);
;     ps = __uint_as_float(rr[0]) + __uint_as_float(rr[1]); }
;   l_reg = l_reg * alpha + ps;
;     ...
;   PK4(p0, 0, pa0); PK4(p0, 8, pa1); PK4(p1, 0, pa2); PK4(p1, 8, pa3);
;     ...
; }
; template <int NQK>
; __device__ __forceinline__ void qkt(f32x16& p0, f32x16& p1, const char* Ks, const bf16x8* qr, int r32, int hi) {
;   constexpr int KROW = NQK * 32 + 16;
;   p0 = f32x16{}; p1 = f32x16{};
; #pragma unroll
;   for (int d0 = 0; d0 < NQK; ++d0) { const int cb = (d0 * 16 + hi * 8) * 2;
;     bf16x8 b0 = *reinterpret_cast<const bf16x8*>(Ks + r32 * KROW + cb);
;     bf16x8 b1 = *reinterpret_cast<const bf16x8*>(Ks + (32 + r32) * KROW + cb);
;     p0 = __builtin_amdgcn_mfma_f32_32x32x16_bf16(b0, qr[d0], p0, 0, 0, 0);
;     p1 = __builtin_amdgcn_mfma_f32_32x32x16_bf16(b1, qr[d0], p1, 0, 0, 0); }
; }
; template <int NQK>
; __device__ __forceinline__ void qkt_mi(f32x16& p0, f32x16& p1, const char* Ks, const bf16x8* qr, int r32, int hi, const f32x16& minit) {
;   constexpr int KROW = NQK * 32 + 16;
; #pragma unroll
;   for (int d0 = 0; d0 < NQK; ++d0) { const int cb = (d0 * 16 + hi * 8) * 2;
;     bf16x8 b0 = *reinterpret_cast<const bf16x8*>(Ks + r32 * KROW + cb);
;     bf16x8 b1 = *reinterpret_cast<const bf16x8*>(Ks + (32 + r32) * KROW + cb);
;     if (d0 == 0) { p0 = __builtin_amdgcn_mfma_f32_32x32x16_bf16(b0, qr[0], minit, 0, 0, 0); p1 = __builtin_amdgcn_mfma_f32_32x32x16_bf16(b1, qr[0], minit, 0, 0, 0); }
;     else { p0 = __builtin_amdgcn_mfma_f32_32x32x16_bf16(b0, qr[d0], p0, 0, 0, 0); p1 = __builtin_amdgcn_mfma_f32_32x32x16_bf16(b1, qr[d0], p1, 0, 0, 0); } }
; }
; __device__ __forceinline__ void decide_mi(f32x16& p0, f32x16& p1, f32x16& minit, float& M, float& alpha, const float thr2, const bool first) {
;   float pmax = p0[0];
; #pragma unroll
;   for (int r = 1; r < 16; ++r) pmax = fmaxf(pmax, p0[r]);
; #pragma unroll
;   for (int r = 0; r < 16; ++r) pmax = fmaxf(pmax, p1[r]);
.LBB0_1286:
	s_mov_b32 s15, s58
	s_mov_b32 s58, s8
	s_mul_i32 s8, s15, 0x2400
	v_add_u32_e32 v215, s8, v221
	ds_read_b128 v[232:235], v215 offset:53760
	ds_read_b128 v[112:115], v215 offset:49152
	ds_read_b128 v[236:239], v215 offset:49184
	v_exp_f32_e32 v96, v96
	v_exp_f32_e32 v97, v97
	v_exp_f32_e32 v99, v99
	s_waitcnt lgkmcnt(1)
	v_mfma_f32_32x32x16_bf16 v[128:143], v[112:115], v[146:149], v[80:95]
	s_waitcnt lgkmcnt(0)
	v_mfma_f32_32x32x16_bf16 v[128:143], v[236:239], v[150:153], v[128:143]
	v_exp_f32_e32 v100, v100
	v_exp_f32_e32 v101, v101
	v_exp_f32_e32 v102, v102
	v_exp_f32_e32 v103, v103
	v_mfma_f32_32x32x16_bf16 v[112:127], v[232:235], v[146:149], v[80:95]
	ds_read_b128 v[232:235], v215 offset:53792
	v_exp_f32_e32 v202, v98
	v_exp_f32_e32 v98, v104
	v_exp_f32_e32 v104, v105
	s_waitcnt lgkmcnt(0)
	v_mfma_f32_32x32x16_bf16 v[112:127], v[232:235], v[150:153], v[112:127]
	ds_read_b128 v[232:235], v215 offset:53824
	ds_read_b128 v[236:239], v215 offset:49216
	v_exp_f32_e32 v105, v106
	v_exp_f32_e32 v106, v107
	v_exp_f32_e32 v107, v108
	s_waitcnt lgkmcnt(0)
	v_mfma_f32_32x32x16_bf16 v[128:143], v[236:239], v[154:157], v[128:143]
	v_exp_f32_e32 v108, v109
	v_exp_f32_e32 v109, v110
	v_exp_f32_e32 v110, v111
	v_mfma_f32_32x32x16_bf16 v[112:127], v[232:235], v[154:157], v[112:127]
	ds_read_b128 v[232:235], v215 offset:53856
	ds_read_b128 v[236:239], v215 offset:49248
	v_add_f32_e32 v111, 0, v175
	v_add_f32_e32 v111, v176, v111
	v_add_f32_e32 v111, v177, v111
	v_add_f32_e32 v111, v178, v111
	v_add_f32_e32 v111, v179, v111
	v_add_f32_e32 v111, v181, v111
	v_add_f32_e32 v111, v183, v111
	v_add_f32_e32 v111, v185, v111
	v_add_f32_e32 v111, v180, v111
	v_add_f32_e32 v111, v182, v111
	v_add_f32_e32 v111, v184, v111
	v_add_f32_e32 v111, v227, v111
	v_add_f32_e32 v111, v228, v111
	v_add_f32_e32 v111, v229, v111
	v_add_f32_e32 v111, v230, v111
	v_add_f32_e32 v111, v174, v111
	v_add_f32_e32 v111, v96, v111
	v_add_f32_e32 v111, v97, v111
	v_add_f32_e32 v111, v202, v111
	v_add_f32_e32 v111, v99, v111
	v_add_f32_e32 v111, v100, v111
	v_add_f32_e32 v111, v101, v111
	v_add_f32_e32 v111, v102, v111
	s_waitcnt lgkmcnt(0)
	v_mfma_f32_32x32x16_bf16 v[128:143], v[236:239], v[158:161], v[128:143]
	v_add_f32_e32 v111, v103, v111
	v_add_f32_e32 v111, v98, v111
	v_add_f32_e32 v111, v104, v111
	v_add_f32_e32 v111, v105, v111
	v_add_f32_e32 v111, v106, v111
	v_add_f32_e32 v111, v107, v111
	v_add_f32_e32 v111, v108, v111
	v_add_f32_e32 v111, v109, v111
	v_add_f32_e32 v224, v110, v111
	s_nop 2
	v_max_f32_e32 v111, v129, v129
	v_max_f32_e32 v226, v128, v128
	v_mfma_f32_32x32x16_bf16 v[112:127], v[232:235], v[158:161], v[112:127]
	v_max_f32_e32 v111, v226, v111
	v_max3_f32 v111, v111, v130, v131
	v_max3_f32 v111, v111, v132, v133
	v_max3_f32 v111, v111, v134, v135
	v_max3_f32 v111, v111, v136, v137
	v_max3_f32 v111, v111, v138, v139
	v_max3_f32 v111, v111, v140, v141
	v_max3_f32 v111, v111, v142, v143
	s_nop 3
	v_max3_f32 v111, v111, v112, v113
	v_max3_f32 v111, v111, v114, v115
	v_max3_f32 v111, v111, v116, v117
	v_max3_f32 v111, v111, v118, v119
	v_max3_f32 v111, v111, v120, v121
	v_max3_f32 v111, v111, v122, v123
	v_max3_f32 v111, v111, v124, v125
	v_max3_f32 v111, v111, v126, v127
	v_mov_b32_e32 v226, v111
	s_nop 1
	v_permlane32_swap_b32_e32 v111, v226
	v_max_f32_e32 v226, v226, v226
	v_max_f32_e32 v111, v111, v111
	v_max_f32_e32 v111, v111, v226
	v_mov_b32_e32 v225, v224
	v_cmp_ge_f32_e32 vcc, s42, v111
	s_nop 0
	v_permlane32_swap_b32_e32 v224, v225
	s_cmp_eq_u64 vcc, exec
	s_cbranch_scc0 .LBB0_1301
	v_mov_b32_e32 v226, 1.0
; #define SBAR() __builtin_amdgcn_sched_barrier(0)
; template <int D0> __device__ __forceinline__ void pv_one_mi(f32x16& od, int vb, bf16x8 pa0, bf16x8 pa1, bf16x8 pa2, bf16x8 pa3, f32x16& q0) {
;   const s16x4 l0 = tr_read<v_rd_off(D0, 0, 0)>(vb), h0 = tr_read<v_rd_off(D0, 0, 1)>(vb), l1 = tr_read<v_rd_off(D0, 1, 0)>(vb), h1 = tr_read<v_rd_off(D0, 1, 1)>(vb);
;   const s16x4 l2 = tr_read<v_rd_off(D0, 2, 0)>(vb), h2 = tr_read<v_rd_off(D0, 2, 1)>(vb), l3 = tr_read<v_rd_off(D0, 3, 0)>(vb), h3 = tr_read<v_rd_off(D0, 3, 1)>(vb);
;   asm volatile("s_waitcnt lgkmcnt(0)" ::: "memory"); SBAR();
;     ...
;   od = __builtin_amdgcn_mfma_f32_32x32x16_bf16(pa0, PK(l0, h0), od, 0, 0, 0);
;   od = __builtin_amdgcn_mfma_f32_32x32x16_bf16(pa1, PK(l1, h1), od, 0, 0, 0);
;   od = __builtin_amdgcn_mfma_f32_32x32x16_bf16(pa2, PK(l2, h2), od, 0, 0, 0);
;   od = __builtin_amdgcn_mfma_f32_32x32x16_bf16(pa3, PK(l3, h3), od, 0, 0, 0);
;     ...
; #pragma unroll
;   for (int r = 4 * D0; r < 4 * D0 + 4; ++r) q0[r] = __builtin_amdgcn_exp2f(q0[r]);
.LBB0_1288:
	v_cvt_pk_bf16_f32 v232, v175, v176
	v_cvt_pk_bf16_f32 v233, v177, v178
	v_cvt_pk_bf16_f32 v234, v179, v181
	v_cvt_pk_bf16_f32 v235, v183, v185
	v_cvt_pk_bf16_f32 v236, v180, v182
	v_cvt_pk_bf16_f32 v237, v184, v227
	v_cvt_pk_bf16_f32 v238, v228, v229
	v_cvt_pk_bf16_f32 v239, v230, v174
	v_cvt_pk_bf16_f32 v228, v96, v97
	v_cvt_pk_bf16_f32 v229, v202, v99
	v_cvt_pk_bf16_f32 v230, v100, v101
	v_cvt_pk_bf16_f32 v231, v102, v103
	v_cvt_pk_bf16_f32 v96, v98, v104
	v_cvt_pk_bf16_f32 v97, v105, v106
	v_cvt_pk_bf16_f32 v98, v107, v108
	v_cvt_pk_bf16_f32 v99, v109, v110
	s_add_i32 s8, s13, 0xfffe8000
	s_add_i32 s9, s12, 0xfffe0000
	s_mov_b32 s38, s30
	s_mov_b32 s39, s31
	s_add_i32 s10, s13, 0xffff0000
	buffer_load_dwordx4 v[174:177], v216, s[28:31], s8 offen
	buffer_load_dwordx4 v[178:181], v216, s[28:31], s10 offen
	buffer_load_dwordx4 v[182:185], v217, s[36:39], s9 offen
	s_lshl_b32 s10, s58, 14
	v_add_u32_e32 v215, s10, v214
	ds_read_b64_tr_b16 v[100:101], v215 offset:0
	ds_read_b64_tr_b16 v[102:103], v215 offset:0x800
	ds_read_b64_tr_b16 v[104:105], v215 offset:0x1000
	ds_read_b64_tr_b16 v[106:107], v215 offset:0x1800
	ds_read_b64_tr_b16 v[108:109], v215 offset:0x2000
	ds_read_b64_tr_b16 v[110:111], v215 offset:0x2800
	ds_read_b64_tr_b16 v[240:241], v215 offset:0x3000
	ds_read_b64_tr_b16 v[242:243], v215 offset:0x3800
	s_waitcnt lgkmcnt(6)
	s_nop 0
	v_mfma_f32_32x32x16_bf16 v[0:15], v[232:235], v[100:103], v[0:15]
	ds_read_b64_tr_b16 v[100:101], v215 offset:0x200
	ds_read_b64_tr_b16 v[102:103], v215 offset:0xa00
	s_waitcnt lgkmcnt(6)
	v_mfma_f32_32x32x16_bf16 v[0:15], v[236:239], v[104:107], v[0:15]
	ds_read_b64_tr_b16 v[104:105], v215 offset:0x1200
	ds_read_b64_tr_b16 v[106:107], v215 offset:0x1a00
	s_waitcnt lgkmcnt(6)
	v_mfma_f32_32x32x16_bf16 v[0:15], v[228:231], v[108:111], v[0:15]
	ds_read_b64_tr_b16 v[108:109], v215 offset:0x2200
	ds_read_b64_tr_b16 v[110:111], v215 offset:0x2a00
	s_waitcnt lgkmcnt(6)
	v_mfma_f32_32x32x16_bf16 v[0:15], v[96:99], v[240:243], v[0:15]
	ds_read_b64_tr_b16 v[240:241], v215 offset:0x3200
	ds_read_b64_tr_b16 v[242:243], v215 offset:0x3a00
	s_waitcnt lgkmcnt(6)
	v_mfma_f32_32x32x16_bf16 v[48:63], v[232:235], v[100:103], v[48:63]
	ds_read_b64_tr_b16 v[100:101], v215 offset:0x400
	ds_read_b64_tr_b16 v[102:103], v215 offset:0xc00
	s_waitcnt lgkmcnt(6)
	v_mfma_f32_32x32x16_bf16 v[48:63], v[236:239], v[104:107], v[48:63]
	ds_read_b64_tr_b16 v[104:105], v215 offset:0x1400
	ds_read_b64_tr_b16 v[106:107], v215 offset:0x1c00
	s_waitcnt lgkmcnt(6)
	v_mfma_f32_32x32x16_bf16 v[48:63], v[228:231], v[108:111], v[48:63]
	ds_read_b64_tr_b16 v[108:109], v215 offset:0x2400
	ds_read_b64_tr_b16 v[110:111], v215 offset:0x2c00
	s_waitcnt lgkmcnt(6)
	v_mfma_f32_32x32x16_bf16 v[48:63], v[96:99], v[240:243], v[48:63]
	ds_read_b64_tr_b16 v[240:241], v215 offset:0x3400
	ds_read_b64_tr_b16 v[242:243], v215 offset:0x3c00
	s_waitcnt lgkmcnt(6)
	v_mfma_f32_32x32x16_bf16 v[32:47], v[232:235], v[100:103], v[32:47]
	ds_read_b64_tr_b16 v[100:101], v215 offset:0x600
	ds_read_b64_tr_b16 v[102:103], v215 offset:0xe00
	s_waitcnt lgkmcnt(6)
	v_mfma_f32_32x32x16_bf16 v[32:47], v[236:239], v[104:107], v[32:47]
	ds_read_b64_tr_b16 v[104:105], v215 offset:0x1600
	ds_read_b64_tr_b16 v[106:107], v215 offset:0x1e00
	s_waitcnt lgkmcnt(6)
	v_mfma_f32_32x32x16_bf16 v[32:47], v[228:231], v[108:111], v[32:47]
	ds_read_b64_tr_b16 v[108:109], v215 offset:0x2600
	ds_read_b64_tr_b16 v[110:111], v215 offset:0x2e00
	s_waitcnt lgkmcnt(6)
	v_mfma_f32_32x32x16_bf16 v[32:47], v[96:99], v[240:243], v[32:47]
	ds_read_b64_tr_b16 v[240:241], v215 offset:0x3600
	ds_read_b64_tr_b16 v[242:243], v215 offset:0x3e00
	s_waitcnt lgkmcnt(0)
	v_mfma_f32_32x32x16_bf16 v[16:31], v[232:235], v[100:103], v[16:31]
	s_waitcnt vmcnt(3)
	s_lshl_b32 s16, s59, 14
	v_add_u32_e32 v100, s16, v218
	s_mul_i32 s11, s59, 0x2400
	s_waitcnt vmcnt(5)
	ds_write_b128 v100, v[162:165]
	s_waitcnt vmcnt(4)
	ds_write_b128 v100, v[166:169] offset:8192
	v_add_u32_e32 v100, s11, v219
	v_cmp_gt_f32_e32 vcc, 1.0, v226
	v_mfma_f32_32x32x16_bf16 v[16:31], v[236:239], v[104:107], v[16:31]
	s_waitcnt vmcnt(3)
	ds_write_b128 v100, v[170:173] offset:49152
	v_mfma_f32_32x32x16_bf16 v[16:31], v[228:231], v[108:111], v[16:31]
	v_mfma_f32_32x32x16_bf16 v[16:31], v[96:99], v[240:243], v[16:31]
	s_cbranch_vccz .LBB0_1292
	s_and_saveexec_b64 s[8:9], s[6:7]
	ds_write_b32 v199, v226 offset:128
	s_or_b64 exec, exec, s[8:9]
	s_waitcnt lgkmcnt(0)
	v_add_u32_e32 v108, v191, v198
	ds_read_b128 v[96:99], v108 offset:224
	ds_read_b128 v[100:103], v108 offset:192
	ds_read_b128 v[104:107], v108 offset:160
	ds_read_b128 v[108:111], v108 offset:128
	s_waitcnt lgkmcnt(3)
	v_pk_mul_f32 v[12:13], v[12:13], v[96:97]
	s_waitcnt lgkmcnt(2)
	v_pk_mul_f32 v[8:9], v[8:9], v[100:101]
	s_waitcnt lgkmcnt(1)
	v_pk_mul_f32 v[4:5], v[4:5], v[104:105]
	v_pk_mul_f32 v[14:15], v[14:15], v[98:99]
	v_pk_mul_f32 v[10:11], v[10:11], v[102:103]
	v_pk_mul_f32 v[6:7], v[6:7], v[106:107]
	s_waitcnt lgkmcnt(0)
	v_pk_mul_f32 v[2:3], v[2:3], v[110:111]
	v_pk_mul_f32 v[0:1], v[0:1], v[108:109]
	v_pk_mul_f32 v[60:61], v[60:61], v[96:97]
	v_pk_mul_f32 v[56:57], v[56:57], v[100:101]
	v_pk_mul_f32 v[52:53], v[52:53], v[104:105]
	v_pk_mul_f32 v[62:63], v[62:63], v[98:99]
	v_pk_mul_f32 v[58:59], v[58:59], v[102:103]
	v_pk_mul_f32 v[54:55], v[54:55], v[106:107]
	v_pk_mul_f32 v[50:51], v[50:51], v[110:111]
	v_pk_mul_f32 v[48:49], v[48:49], v[108:109]
	v_pk_mul_f32 v[44:45], v[44:45], v[96:97]
	v_pk_mul_f32 v[40:41], v[40:41], v[100:101]
	v_pk_mul_f32 v[36:37], v[36:37], v[104:105]
	v_pk_mul_f32 v[46:47], v[46:47], v[98:99]
	v_pk_mul_f32 v[42:43], v[42:43], v[102:103]
	v_pk_mul_f32 v[38:39], v[38:39], v[106:107]
	v_pk_mul_f32 v[34:35], v[34:35], v[110:111]
	v_pk_mul_f32 v[32:33], v[32:33], v[108:109]
	v_pk_mul_f32 v[28:29], v[28:29], v[96:97]
	v_pk_mul_f32 v[24:25], v[24:25], v[100:101]
	v_pk_mul_f32 v[20:21], v[20:21], v[104:105]
	v_pk_mul_f32 v[30:31], v[30:31], v[98:99]
	v_pk_mul_f32 v[26:27], v[26:27], v[102:103]
	v_pk_mul_f32 v[22:23], v[22:23], v[106:107]
	v_pk_mul_f32 v[18:19], v[18:19], v[110:111]
	v_pk_mul_f32 v[16:17], v[16:17], v[108:109]

; #define LAS __attribute__((address_space(3)))
; __device__ __forceinline__ unsigned xb_ld(unsigned* p)              { return __hip_atomic_load(p, __ATOMIC_RELAXED, __HIP_MEMORY_SCOPE_AGENT); }
; __device__ __forceinline__ unsigned xb_xcc_id() { return (unsigned)__builtin_amdgcn_s_getreg((3 << 11) | 20) & 0xFu; }
; __device__ __forceinline__ void xcd_barrier_complete(unsigned* bar, unsigned x, unsigned& nloc, unsigned& nx) {
;   const unsigned G = gridDim.x;
;   unsigned sum, cnt, mine, sp = 0u;
;   for (;;) {
;     sum = 0u; cnt = 0u; mine = 0u;
; #pragma unroll
;     for (unsigned j = 0; j < 16; ++j) { const unsigned c = xb_ld(&bar[XB_XCNT(j)]); sum += c; cnt += (c > 0u) ? 1u : 0u; mine = (j == x) ? c : mine; }
; __device__ __forceinline__ void grid_sync(unsigned* bar, volatile LAS unsigned* st) {
;   asm volatile("s_waitcnt vmcnt(0)" ::: "memory");
;   __syncthreads();
;   if (threadIdx.x == 0) {
;     __builtin_amdgcn_s_waitcnt(0);
;     const unsigned x = xb_xcc_id();
;     unsigned nloc = st[0], nx = st[1];
;     if (nloc == 0u) { xcd_barrier_complete(bar, x, nloc, nx); st[0] = nloc; st[1] = nx; }
.LBB0_1314:
	s_mov_b64 s[8:9], exec
	s_mov_b64 exec, -1
	v_mov_b32_e32 v202, 0x1000
	s_mov_b64 exec, s[8:9]
	s_mov_b64 s[8:9], s[0:1]
	s_waitcnt vmcnt(0)
	s_barrier
	s_mov_b64 s[6:7], exec
	v_readlane_b32 s10, v255, 17
	v_readlane_b32 s11, v255, 18
	v_readlane_b32 s68, v255, 20
	v_readlane_b32 s44, v255, 32
	s_and_b64 s[10:11], s[6:7], s[10:11]
	s_movk_i32 s90, 0x300
	s_movk_i32 s91, 0x60
	s_mov_b32 s88, 0x30000
	s_mov_b32 s89, 0xe000
	s_movk_i32 s40, 0x70
	s_movk_i32 s41, 0x50
	v_readlane_b32 s69, v255, 21
	v_readlane_b32 s45, v255, 33
	s_mov_b64 exec, s[10:11]
	s_cbranch_execz .LBB0_1367
	s_load_dwordx2 s[8:9], s[8:9], 0xd8
	s_waitcnt vmcnt(0) expcnt(0) lgkmcnt(0)
	s_getreg_b32 s10, hwreg(HW_REG_XCC_ID, 0, 4)
	ds_read_b32 v2, v144
	ds_read_b32 v0, v144 offset:4
	s_and_b32 s51, s10, 15
	s_waitcnt lgkmcnt(1)
	v_cmp_ne_u32_e32 vcc, 0, v2
	s_cbranch_vccnz .LBB0_1331
	s_add_u32 s10, s8, 0x9bca300
	s_addc_u32 s11, s9, 0
	s_add_u32 s12, s8, 0x9bca500
	s_addc_u32 s13, s9, 0
	s_add_u32 s14, s8, 0x9bca600
	s_addc_u32 s15, s9, 0
	s_add_u32 s16, s8, 0x9bca700
	s_addc_u32 s17, s9, 0
	s_add_u32 s18, s8, 0x9bca800
	s_addc_u32 s19, s9, 0
	s_add_u32 s20, s8, 0x9bca900
	s_addc_u32 s21, s9, 0
	s_add_u32 s22, s8, 0x9bcaa00
	s_addc_u32 s23, s9, 0
	s_add_u32 s28, s8, 0x9bcab00
	s_addc_u32 s29, s9, 0
	s_add_u32 s36, s8, 0x9bcac00
	s_addc_u32 s37, s9, 0
	s_add_u32 s38, s8, 0x9bcad00
	s_addc_u32 s39, s9, 0
	s_add_u32 s84, s8, 0x9bcae00
	s_addc_u32 s85, s9, 0
	s_add_u32 s68, s8, 0x9bcaf00
	s_addc_u32 s69, s9, 0
	s_add_u32 s74, s8, 0x9bcb000
	s_addc_u32 s75, s9, 0
	s_add_u32 s44, s8, 0x9bcb100
	s_addc_u32 s45, s9, 0
	s_add_u32 s58, s8, 0x9bcb200
	s_addc_u32 s59, s9, 0
	s_add_u32 s86, s8, 0x9bcb300
	s_addc_u32 s87, s9, 0
	s_add_u32 s88, s8, 0x9bcb400
	s_addc_u32 s89, s9, 0
	s_mov_b32 s76, 1
	s_branch .LBB0_1319
